# attention: removed mid-chain accumulator move (8 v_mov_b64 + s_nop stall) by reordering the last QK MFMA of the second chain; plus no-op add/max trims
# baseline (speedup 1.0000x reference)
.LBB0_517:
	ds_read_b128 v[112:115], v165 offset:9216
	ds_read_b128 v[116:119], v165 offset:9248
	v_exp_f32_e32 v206, v48
	v_exp_f32_e32 v208, v49
	v_exp_f32_e32 v210, v50
	v_exp_f32_e32 v212, v51
	v_exp_f32_e32 v214, v52
	v_exp_f32_e32 v216, v53
	v_exp_f32_e32 v218, v54
	s_waitcnt lgkmcnt(1)
	v_mfma_f32_32x32x16_bf16 v[96:111], v[112:115], v[130:133], v[32:47]
	ds_read_b128 v[178:181], v165 offset:13824
	ds_read_b128 v[182:185], v165 offset:13856
	ds_read_b128 v[112:115], v165 offset:9280
	ds_read_b128 v[194:197], v165 offset:9312
	ds_read_b128 v[198:201], v165 offset:13888
	ds_read_b128 v[202:205], v165 offset:13920
	v_exp_f32_e32 v220, v55
	ds_read_b64_tr_b16 v[48:49], v175 offset:18432
	ds_read_b64_tr_b16 v[50:51], v175 offset:19968
	ds_read_b64_tr_b16 v[54:55], v175 offset:20032
	ds_read_b64_tr_b16 v[52:53], v175 offset:18496
	v_exp_f32_e32 v222, v66
	v_exp_f32_e32 v224, v67
	v_cvt_pk_bf16_f32 v66, v214, v216
	v_cvt_pk_bf16_f32 v67, v218, v220
	s_waitcnt lgkmcnt(10)
	v_mfma_f32_32x32x16_bf16 v[96:111], v[116:119], v[134:137], v[96:111]
	v_exp_f32_e32 v207, v56
	v_exp_f32_e32 v209, v57
	v_exp_f32_e32 v211, v58
	v_exp_f32_e32 v213, v59
	v_exp_f32_e32 v215, v60
	v_exp_f32_e32 v217, v61
	v_exp_f32_e32 v219, v62
	s_waitcnt lgkmcnt(7)
	v_mfma_f32_32x32x16_bf16 v[96:111], v[112:115], v[138:141], v[96:111]
	s_waitcnt lgkmcnt(6)
	v_mfma_f32_32x32x16_bf16 v[96:111], v[194:197], v[150:153], v[96:111]
	v_exp_f32_e32 v221, v63
	v_exp_f32_e32 v226, v68
	v_exp_f32_e32 v228, v69
	v_exp_f32_e32 v223, v74
	v_exp_f32_e32 v225, v75
	v_exp_f32_e32 v227, v76
	v_exp_f32_e32 v229, v77
	v_mfma_f32_32x32x16_bf16 v[112:127], v[178:181], v[130:133], v[32:47]
	v_exp_f32_e32 v178, v64
	v_exp_f32_e32 v180, v65
	v_cvt_pk_bf16_f32 v64, v206, v208
	v_cvt_pk_bf16_f32 v65, v210, v212
	v_exp_f32_e32 v179, v72
	v_exp_f32_e32 v181, v73
	ds_read_b64_tr_b16 v[56:57], v175 offset:21504
	ds_read_b64_tr_b16 v[58:59], v175 offset:23040
	ds_read_b64_tr_b16 v[62:63], v175 offset:23104
	ds_read_b64_tr_b16 v[60:61], v175 offset:21568
	v_mfma_f32_32x32x16_bf16 v[112:127], v[182:185], v[134:137], v[112:127]
	v_exp_f32_e32 v182, v70
	v_exp_f32_e32 v184, v71
	v_exp_f32_e32 v183, v78
	v_exp_f32_e32 v185, v79
	v_pk_add_f32 v[194:195], v[206:207], v[208:209]
	v_pk_add_f32 v[196:197], v[210:211], v[212:213]
	v_cvt_pk_bf16_f32 v68, v207, v209
	s_waitcnt lgkmcnt(9)
	v_mfma_f32_32x32x16_bf16 v[112:127], v[198:201], v[138:141], v[112:127]
	v_cvt_pk_bf16_f32 v69, v211, v213
	v_cvt_pk_bf16_f32 v70, v215, v217
	v_cvt_pk_bf16_f32 v71, v219, v221
	v_cvt_pk_bf16_f32 v72, v178, v180
	v_cvt_pk_bf16_f32 v76, v179, v181
	v_pk_add_f32 v[178:179], v[178:179], v[180:181]
	v_cvt_pk_bf16_f32 v73, v222, v224
	s_waitcnt lgkmcnt(6)
	v_mfma_f32_32x32x16_bf16 v[16:31], v[48:51], v[64:67], v[16:31]
	v_add_f32_e64 v48, v194, v196
	v_add_f32_e64 v49, v195, v197
	v_add_f32_e64 v50, v214, v216
	v_add_f32_e64 v51, v215, v217
	v_add_f32_e64 v194, v218, v220
	v_add_f32_e64 v195, v219, v221
	v_pk_add_f32 v[50:51], v[50:51], v[194:195]
	v_cvt_pk_bf16_f32 v74, v226, v228
	s_waitcnt lgkmcnt(4)
	v_mfma_f32_32x32x16_bf16 v[0:15], v[52:55], v[64:67], v[0:15]
	v_add_f32_e64 v52, v222, v224
	v_add_f32_e64 v53, v223, v225
	v_add_f32_e64 v54, v226, v228
	v_add_f32_e64 v55, v227, v229
	v_add_f32_e64 v64, v182, v184
	v_add_f32_e64 v65, v183, v185
	v_pk_add_f32 v[52:53], v[178:179], v[52:53]
	v_pk_add_f32 v[54:55], v[54:55], v[64:65]
	v_pk_add_f32 v[48:49], v[48:49], v[52:53]
	v_pk_add_f32 v[50:51], v[50:51], v[54:55]
	v_mfma_f32_32x32x16_bf16 v[112:127], v[202:205], v[150:153], v[112:127]
	v_add_f32_e64 v48, v48, v50
	v_add_f32_e64 v49, v49, v51
	v_max3_f32 v52, v96, v97, v98
	v_max_f32_e32 v53, v99, v100
	v_add_f32_e32 v64, v48, v49
	ds_read_b64_tr_b16 v[48:49], v175 offset:24576
	ds_read_b64_tr_b16 v[50:51], v175 offset:26112
	s_waitcnt lgkmcnt(4)
	v_mfma_f32_32x32x16_bf16 v[16:31], v[56:59], v[68:71], v[16:31]
	v_max3_f32 v58, v52, v102, v103
	v_max3_f32 v59, v53, v101, v104
	ds_read_b64_tr_b16 v[54:55], v175 offset:26176
	ds_read_b64_tr_b16 v[52:53], v175 offset:24640
	v_cvt_pk_bf16_f32 v75, v182, v184
	v_max3_f32 v56, v112, v113, v114
	v_max3_f32 v57, v115, v116, v117
	v_cvt_pk_bf16_f32 v77, v223, v225
	s_waitcnt lgkmcnt(4)
	v_mfma_f32_32x32x16_bf16 v[0:15], v[60:63], v[68:71], v[0:15]
	v_cvt_pk_bf16_f32 v78, v227, v229
	v_cvt_pk_bf16_f32 v79, v183, v185
	s_waitcnt lgkmcnt(2)
	v_mfma_f32_32x32x16_bf16 v[16:31], v[48:51], v[72:75], v[16:31]
	v_max3_f32 v48, v56, v118, v119
	v_max3_f32 v49, v57, v120, v121
	v_max3_f32 v50, v58, v106, v107
	v_max3_f32 v51, v59, v105, v108
	v_max3_f32 v48, v48, v122, v123
	v_max3_f32 v49, v49, v124, v125
	v_max3_f32 v50, v50, v110, v111
	s_waitcnt lgkmcnt(0)
	v_mfma_f32_32x32x16_bf16 v[0:15], v[52:55], v[72:75], v[0:15]
	v_max3_f32 v48, v48, v126, v127
	v_max3_f32 v49, v51, v109, v49
	ds_read_b64_tr_b16 v[56:57], v175 offset:27648
	ds_read_b64_tr_b16 v[58:59], v175 offset:29184
	v_max3_f32 v48, v50, v48, v49
	ds_read_b64_tr_b16 v[52:53], v175 offset:29248
	ds_read_b64_tr_b16 v[50:51], v175 offset:27712
	v_mov_b32_e32 v49, v48
	v_cndmask_b32_e64 v54, 0, 1, s[2:3]
	s_waitcnt lgkmcnt(2)
	v_mfma_f32_32x32x16_bf16 v[16:31], v[56:59], v[76:79], v[16:31]
	v_permlane32_swap_b32_e32 v48, v49
	v_add_f32_e32 v176, v176, v64
	v_cmp_ne_u32_e64 s[4:5], 1, v54
	s_waitcnt lgkmcnt(0)
	v_mfma_f32_32x32x16_bf16 v[0:15], v[50:53], v[76:79], v[0:15]
	s_andn2_b64 vcc, exec, s[2:3]
	s_cbranch_vccnz .LBB0_519
	v_max_f32_e32 v48, v48, v49
	v_cmp_lt_f32_e32 vcc, s45, v48
	s_cbranch_vccnz .LBB0_533

.LBB0_527:
	ds_read_b128 v[64:67], v165
	ds_read_b128 v[68:71], v165 offset:32
	ds_read_b128 v[72:75], v165 offset:4608
	ds_read_b128 v[76:79], v165 offset:4640
	v_exp_f32_e32 v194, v96
	s_waitcnt lgkmcnt(3)
	v_mfma_f32_32x32x16_bf16 v[48:63], v[64:67], v[130:133], v[32:47]
	ds_read_b128 v[64:67], v165 offset:64
	ds_read_b128 v[160:163], v165 offset:96
	ds_read_b128 v[178:181], v165 offset:4672
	ds_read_b128 v[182:185], v165 offset:4704
	v_exp_f32_e32 v196, v97
	v_exp_f32_e32 v198, v98
	v_exp_f32_e32 v200, v99
	v_exp_f32_e32 v202, v100
	v_exp_f32_e32 v204, v101
	v_exp_f32_e32 v206, v102
	s_waitcnt lgkmcnt(5)
	v_mfma_f32_32x32x16_bf16 v[80:95], v[72:75], v[130:133], v[32:47]
	v_exp_f32_e32 v208, v103
	v_exp_f32_e32 v195, v104
	v_exp_f32_e32 v197, v105
	v_exp_f32_e32 v199, v106
	v_exp_f32_e32 v201, v107
	v_exp_f32_e32 v203, v108
	v_exp_f32_e32 v205, v109
	s_waitcnt lgkmcnt(4)
	v_mfma_f32_32x32x16_bf16 v[80:95], v[76:79], v[134:137], v[80:95]
	v_exp_f32_e32 v207, v110
	v_exp_f32_e32 v209, v111
	ds_read_b64_tr_b16 v[96:97], v175 offset:30720
	ds_read_b64_tr_b16 v[98:99], v175 offset:32256
	ds_read_b64_tr_b16 v[102:103], v175 offset:32320
	ds_read_b64_tr_b16 v[100:101], v175 offset:30784
	ds_read_b64_tr_b16 v[104:105], v175 offset:33792
	ds_read_b64_tr_b16 v[106:107], v175 offset:35328
	ds_read_b64_tr_b16 v[110:111], v175 offset:35392
	ds_read_b64_tr_b16 v[108:109], v175 offset:33856
	v_exp_f32_e32 v112, v112
	v_exp_f32_e32 v210, v113
	v_exp_f32_e32 v114, v114
	v_exp_f32_e32 v212, v115
	v_mfma_f32_32x32x16_bf16 v[48:63], v[68:71], v[134:137], v[48:63]
	v_exp_f32_e32 v113, v120
	v_exp_f32_e32 v211, v121
	v_exp_f32_e32 v115, v122
	v_exp_f32_e32 v213, v123
	v_exp_f32_e32 v116, v116
	v_exp_f32_e32 v214, v117
	v_exp_f32_e32 v118, v118
	s_waitcnt lgkmcnt(8)
	v_mfma_f32_32x32x16_bf16 v[80:95], v[178:181], v[138:141], v[80:95]
	v_mfma_f32_32x32x16_bf16 v[48:63], v[64:67], v[138:141], v[48:63]
	v_mfma_f32_32x32x16_bf16 v[64:79], v[182:185], v[150:153], v[80:95]
	v_mfma_f32_32x32x16_bf16 v[48:63], v[160:163], v[150:153], v[48:63]
	v_exp_f32_e32 v216, v119
	v_exp_f32_e32 v117, v124
	v_exp_f32_e32 v215, v125
	v_exp_f32_e32 v119, v126
	v_exp_f32_e32 v217, v127
	v_pk_add_f32 v[120:121], v[206:207], v[208:209]
	s_and_b64 vcc, exec, s[2:3]
	s_nop 1
	v_cvt_pk_bf16_f32 v80, v194, v196
	v_cvt_pk_bf16_f32 v81, v198, v200
	v_cvt_pk_bf16_f32 v82, v202, v204
	v_cvt_pk_bf16_f32 v83, v206, v208
	v_cvt_pk_bf16_f32 v84, v195, v197
	v_cvt_pk_bf16_f32 v85, v199, v201
	v_cvt_pk_bf16_f32 v86, v203, v205
	v_cvt_pk_bf16_f32 v87, v207, v209
	v_cvt_pk_bf16_f32 v88, v112, v210
	v_cvt_pk_bf16_f32 v89, v114, v212
	v_cvt_pk_bf16_f32 v90, v116, v214
	s_waitcnt lgkmcnt(6)
	v_mfma_f32_32x32x16_bf16 v[16:31], v[96:99], v[80:83], v[16:31]
	v_add_f32_e64 v96, v194, v196
	v_add_f32_e64 v97, v195, v197
	v_add_f32_e64 v98, v198, v200
	v_add_f32_e64 v99, v199, v201
	v_cvt_pk_bf16_f32 v91, v118, v216
	v_pk_add_f32 v[96:97], v[96:97], v[98:99]
	v_pk_add_f32 v[98:99], v[202:203], v[204:205]
	v_pk_add_f32 v[98:99], v[98:99], v[120:121]
	s_waitcnt lgkmcnt(4)
	v_mfma_f32_32x32x16_bf16 v[0:15], v[100:103], v[80:83], v[0:15]
	v_add_f32_e64 v80, v98, 0
	v_add_f32_e64 v81, v99, 0
	v_add_f32_e64 v82, v112, v210
	v_add_f32_e64 v83, v113, v211
	v_add_f32_e64 v98, v114, v212
	v_add_f32_e64 v99, v115, v213
	v_pk_add_f32 v[100:101], v[118:119], v[216:217]
	v_pk_add_f32 v[82:83], v[82:83], v[98:99]
	v_pk_add_f32 v[98:99], v[116:117], v[214:215]
	v_pk_add_f32 v[82:83], v[82:83], v[96:97]
	v_add_f32_e64 v98, v98, v100
	v_add_f32_e64 v99, v99, v101
	v_max3_f32 v97, v48, v49, v50
	v_add_f32_e64 v80, v98, v80
	v_add_f32_e64 v81, v99, v81
	v_cvt_pk_bf16_f32 v92, v113, v211
	v_pk_add_f32 v[80:81], v[82:83], v[80:81]
	v_cvt_pk_bf16_f32 v93, v115, v213
	v_add_f32_e32 v96, v80, v81
	s_waitcnt lgkmcnt(2)
	v_mfma_f32_32x32x16_bf16 v[16:31], v[104:107], v[84:87], v[16:31]
	ds_read_b64_tr_b16 v[80:81], v175 offset:36864
	ds_read_b64_tr_b16 v[82:83], v175 offset:38400
	v_max3_f32 v99, v64, v65, v66
	v_max3_f32 v100, v67, v68, v69
	v_cvt_pk_bf16_f32 v94, v117, v215
	v_cvt_pk_bf16_f32 v95, v119, v217
	v_add_f32_e32 v176, v176, v96
	s_waitcnt lgkmcnt(2)
	v_mfma_f32_32x32x16_bf16 v[0:15], v[108:111], v[84:87], v[0:15]
	v_max_f32_e32 v98, v51, v52
	ds_read_b64_tr_b16 v[86:87], v175 offset:38464
	ds_read_b64_tr_b16 v[84:85], v175 offset:36928
	s_waitcnt lgkmcnt(2)
	v_mfma_f32_32x32x16_bf16 v[16:31], v[80:83], v[88:91], v[16:31]
	v_max3_f32 v80, v97, v54, v55
	v_max3_f32 v97, v98, v53, v56
	v_max3_f32 v98, v99, v70, v71
	v_max3_f32 v99, v100, v72, v73
	v_max3_f32 v100, v80, v58, v59
	ds_read_b64_tr_b16 v[80:81], v175 offset:39936
	ds_read_b64_tr_b16 v[82:83], v175 offset:41472
	s_waitcnt lgkmcnt(2)
	v_mfma_f32_32x32x16_bf16 v[0:15], v[84:87], v[88:91], v[0:15]
	v_max3_f32 v84, v98, v74, v75
	v_max3_f32 v91, v84, v78, v79
	ds_read_b64_tr_b16 v[86:87], v175 offset:41536
	ds_read_b64_tr_b16 v[84:85], v175 offset:40000
	v_max3_f32 v88, v97, v57, v60
	v_max3_f32 v89, v99, v76, v77
	v_max3_f32 v90, v100, v62, v63
	s_waitcnt lgkmcnt(2)
	v_mfma_f32_32x32x16_bf16 v[16:31], v[80:83], v[92:95], v[16:31]
	v_max3_f32 v80, v88, v61, v89
	v_max3_f32 v80, v90, v91, v80
	v_mov_b32_e32 v81, v80
	s_nop 1
	v_permlane32_swap_b32_e32 v80, v81
	s_waitcnt lgkmcnt(0)
	v_mfma_f32_32x32x16_bf16 v[0:15], v[84:87], v[92:95], v[0:15]
	s_cbranch_vccnz .LBB0_529
	v_max_f32_e32 v80, v80, v81
	v_cmp_lt_f32_e32 vcc, s45, v80
	s_cbranch_vccnz .LBB0_534

.LBB0_617:
	ds_read_b128 v[80:83], v202 offset:13312
	ds_read_b128 v[84:87], v202 offset:13344
	s_waitcnt lgkmcnt(1)
	v_mfma_f32_32x32x16_bf16 v[96:111], v[80:83], v[144:147], v[32:47]
	ds_read_b128 v[80:83], v202 offset:19968
	ds_read_b128 v[206:209], v202 offset:20000
	v_exp_f32_e32 v218, v48
	s_waitcnt lgkmcnt(2)
	v_mfma_f32_32x32x16_bf16 v[96:111], v[84:87], v[148:151], v[96:111]
	v_exp_f32_e32 v220, v49
	v_exp_f32_e32 v222, v50
	v_exp_f32_e32 v224, v51
	v_exp_f32_e32 v226, v52
	v_exp_f32_e32 v228, v53
	v_exp_f32_e32 v230, v54
	v_exp_f32_e32 v232, v55
	s_waitcnt lgkmcnt(1)
	v_mfma_f32_32x32x16_bf16 v[112:127], v[80:83], v[144:147], v[32:47]
	ds_read_b128 v[80:83], v202 offset:13376
	ds_read_b128 v[210:213], v202 offset:13408
	ds_read_b128 v[214:217], v202 offset:20032
	ds_read_b128 v[48:51], v202 offset:20064
	v_exp_f32_e32 v219, v56
	v_exp_f32_e32 v221, v57
	v_exp_f32_e32 v223, v58
	v_exp_f32_e32 v225, v59
	s_waitcnt lgkmcnt(4)
	v_mfma_f32_32x32x16_bf16 v[112:127], v[206:209], v[148:151], v[112:127]
	ds_read_b128 v[52:55], v202 offset:13440
	ds_read_b128 v[56:59], v202 offset:13472
	v_exp_f32_e32 v227, v60
	v_exp_f32_e32 v229, v61
	v_exp_f32_e32 v231, v62
	v_exp_f32_e32 v233, v63
	ds_read_b128 v[60:63], v202 offset:20096
	ds_read_b128 v[206:209], v202 offset:20128
	v_exp_f32_e32 v234, v68
	s_waitcnt lgkmcnt(7)
	v_mfma_f32_32x32x16_bf16 v[96:111], v[80:83], v[152:155], v[96:111]
	v_exp_f32_e32 v236, v69
	v_exp_f32_e32 v238, v70
	v_exp_f32_e32 v240, v71
	v_cvt_pk_bf16_f32 v68, v218, v220
	v_cvt_pk_bf16_f32 v69, v222, v224
	v_cvt_pk_bf16_f32 v70, v226, v228
	v_cvt_pk_bf16_f32 v71, v230, v232
	s_waitcnt lgkmcnt(5)
	v_mfma_f32_32x32x16_bf16 v[112:127], v[214:217], v[152:155], v[112:127]
	v_exp_f32_e32 v214, v66
	v_exp_f32_e32 v216, v67
	v_exp_f32_e32 v215, v74
	v_exp_f32_e32 v217, v75
	v_exp_f32_e32 v235, v76
	v_exp_f32_e32 v237, v77
	v_exp_f32_e32 v239, v78
	v_mfma_f32_32x32x16_bf16 v[96:111], v[210:213], v[156:159], v[96:111]
	v_exp_f32_e32 v210, v64
	v_exp_f32_e32 v212, v65
	v_exp_f32_e32 v211, v72
	v_exp_f32_e32 v213, v73
	v_exp_f32_e32 v241, v79
	v_cvt_pk_bf16_f32 v72, v210, v212
	v_cvt_pk_bf16_f32 v73, v214, v216
	s_waitcnt lgkmcnt(4)
	v_mfma_f32_32x32x16_bf16 v[112:127], v[48:51], v[156:159], v[112:127]
	v_cvt_pk_bf16_f32 v74, v234, v236
	v_cvt_pk_bf16_f32 v75, v238, v240
	v_cvt_pk_bf16_f32 v76, v211, v213
	v_cvt_pk_bf16_f32 v77, v215, v217
	v_cvt_pk_bf16_f32 v78, v235, v237
	v_cvt_pk_bf16_f32 v79, v239, v241
	s_waitcnt lgkmcnt(3)
	v_mfma_f32_32x32x16_bf16 v[96:111], v[52:55], v[160:163], v[96:111]
	ds_read_b64_tr_b16 v[48:49], v175 offset:26624
	ds_read_b64_tr_b16 v[50:51], v175 offset:28160
	ds_read_b64_tr_b16 v[54:55], v175 offset:28224
	ds_read_b64_tr_b16 v[52:53], v175 offset:26688
	s_waitcnt lgkmcnt(5)
	v_mfma_f32_32x32x16_bf16 v[112:127], v[60:63], v[160:163], v[112:127]
	ds_read_b64_tr_b16 v[60:61], v175 offset:29696
	ds_read_b64_tr_b16 v[62:63], v175 offset:31232
	ds_read_b64_tr_b16 v[66:67], v175 offset:31296
	ds_read_b64_tr_b16 v[64:65], v175 offset:29760
	s_andn2_b64 vcc, exec, s[8:9]
	s_waitcnt lgkmcnt(6)
	v_mfma_f32_32x32x16_bf16 v[16:31], v[48:51], v[68:71], v[16:31]
	v_add_f32_e64 v50, v226, v228
	v_add_f32_e64 v51, v227, v229
	s_waitcnt lgkmcnt(4)
	v_mfma_f32_32x32x16_bf16 v[0:15], v[52:55], v[68:71], v[0:15]
	v_add_f32_e64 v52, v214, v216
	v_add_f32_e64 v53, v215, v217
	v_add_f32_e64 v54, v234, v236
	v_add_f32_e64 v55, v235, v237
	v_add_f32_e64 v68, v238, v240
	v_add_f32_e64 v69, v239, v241
	v_pk_add_f32 v[54:55], v[54:55], v[68:69]
	v_mfma_f32_32x32x16_bf16 v[96:111], v[56:59], v[164:167], v[96:111]
	v_cvt_pk_bf16_f32 v56, v219, v221
	v_cvt_pk_bf16_f32 v57, v223, v225
	v_cvt_pk_bf16_f32 v58, v227, v229
	v_cvt_pk_bf16_f32 v59, v231, v233
	v_mfma_f32_32x32x16_bf16 v[112:127], v[206:209], v[164:167], v[112:127]
	v_add_f32_e64 v206, v218, v220
	v_add_f32_e64 v207, v219, v221
	v_add_f32_e64 v208, v222, v224
	v_add_f32_e64 v209, v223, v225
	v_add_f32_e64 v48, v206, v208
	v_add_f32_e64 v49, v207, v209
	v_pk_add_f32 v[206:207], v[230:231], v[232:233]
	v_pk_add_f32 v[50:51], v[50:51], v[206:207]
	v_pk_add_f32 v[206:207], v[210:211], v[212:213]
	v_pk_add_f32 v[52:53], v[206:207], v[52:53]
	s_waitcnt lgkmcnt(2)
	v_mfma_f32_32x32x16_bf16 v[16:31], v[60:63], v[56:59], v[16:31]
	v_add_f32_e64 v48, v48, v52
	v_add_f32_e64 v49, v49, v53
	v_add_f32_e64 v50, v50, v54
	v_add_f32_e64 v51, v51, v55
	v_pk_add_f32 v[48:49], v[48:49], v[50:51]
	v_max3_f32 v52, v96, v97, v98
	v_max_f32_e32 v53, v99, v100
	s_waitcnt lgkmcnt(0)
	v_mfma_f32_32x32x16_bf16 v[0:15], v[64:67], v[56:59], v[0:15]
	v_add_f32_e32 v60, v48, v49
	ds_read_b64_tr_b16 v[48:49], v175 offset:32768
	ds_read_b64_tr_b16 v[50:51], v175 offset:34304
	v_max3_f32 v58, v52, v102, v103
	v_max3_f32 v59, v53, v101, v104
	ds_read_b64_tr_b16 v[54:55], v175 offset:34368
	ds_read_b64_tr_b16 v[52:53], v175 offset:32832
	v_max3_f32 v56, v112, v113, v114
	v_max3_f32 v57, v115, v116, v117
	s_waitcnt lgkmcnt(2)
	v_mfma_f32_32x32x16_bf16 v[16:31], v[48:51], v[72:75], v[16:31]
	v_max3_f32 v48, v56, v118, v119
	v_max3_f32 v49, v57, v120, v121
	v_max3_f32 v50, v58, v106, v107
	v_max3_f32 v51, v59, v105, v108
	v_max3_f32 v48, v48, v122, v123
	v_max3_f32 v49, v49, v124, v125
	v_max3_f32 v50, v50, v110, v111
	s_waitcnt lgkmcnt(0)
	v_mfma_f32_32x32x16_bf16 v[0:15], v[52:55], v[72:75], v[0:15]
	v_max3_f32 v48, v48, v126, v127
	v_max3_f32 v49, v51, v109, v49
	ds_read_b64_tr_b16 v[56:57], v175 offset:35840
	ds_read_b64_tr_b16 v[58:59], v175 offset:37376
	v_max3_f32 v48, v50, v48, v49
	ds_read_b64_tr_b16 v[52:53], v175 offset:37440
	ds_read_b64_tr_b16 v[50:51], v175 offset:35904
	v_mov_b32_e32 v49, v48
	v_cndmask_b32_e64 v54, 0, 1, s[8:9]
	s_waitcnt lgkmcnt(2)
	v_mfma_f32_32x32x16_bf16 v[16:31], v[56:59], v[76:79], v[16:31]
	v_permlane32_swap_b32_e32 v48, v49
	v_add_f32_e32 v205, v205, v60
	v_cmp_ne_u32_e64 s[10:11], 1, v54
	s_waitcnt lgkmcnt(0)
	v_mfma_f32_32x32x16_bf16 v[0:15], v[50:53], v[76:79], v[0:15]
	s_cbranch_vccnz .LBB0_619
	v_max_f32_e32 v48, v48, v49
	v_cmp_lt_f32_e32 vcc, s45, v48
	s_cbranch_vccnz .LBB0_649

.LBB0_639:
	ds_read_b128 v[64:67], v202
	ds_read_b128 v[68:71], v202 offset:32
	v_exp_f32_e32 v184, v96
	v_exp_f32_e32 v206, v97
	v_exp_f32_e32 v208, v98
	s_waitcnt lgkmcnt(1)
	v_mfma_f32_32x32x16_bf16 v[48:63], v[64:67], v[144:147], v[32:47]
	v_exp_f32_e32 v210, v99
	v_exp_f32_e32 v212, v100
	v_exp_f32_e32 v214, v101
	v_exp_f32_e32 v216, v102
	v_exp_f32_e32 v218, v103
	v_exp_f32_e32 v185, v104
	v_exp_f32_e32 v207, v105
	s_waitcnt lgkmcnt(0)
	v_mfma_f32_32x32x16_bf16 v[48:63], v[68:71], v[148:151], v[48:63]
	ds_read_b128 v[64:67], v202 offset:6656
	ds_read_b128 v[68:71], v202 offset:6688
	v_exp_f32_e32 v209, v106
	v_exp_f32_e32 v211, v107
	v_exp_f32_e32 v213, v108
	v_exp_f32_e32 v215, v109
	v_exp_f32_e32 v217, v110
	v_exp_f32_e32 v219, v111
	s_waitcnt lgkmcnt(1)
	v_mfma_f32_32x32x16_bf16 v[80:95], v[64:67], v[144:147], v[32:47]
	ds_read_b128 v[64:67], v202 offset:64
	ds_read_b128 v[72:75], v202 offset:96
	v_exp_f32_e32 v220, v112
	v_exp_f32_e32 v222, v113
	v_exp_f32_e32 v224, v114
	v_exp_f32_e32 v226, v115
	v_exp_f32_e32 v228, v116
	v_exp_f32_e32 v230, v117
	s_waitcnt lgkmcnt(1)
	v_mfma_f32_32x32x16_bf16 v[48:63], v[64:67], v[152:155], v[48:63]
	ds_read_b128 v[64:67], v202 offset:6720
	v_exp_f32_e32 v232, v118
	v_exp_f32_e32 v234, v119
	v_exp_f32_e32 v221, v120
	v_exp_f32_e32 v223, v121
	v_exp_f32_e32 v225, v122
	v_exp_f32_e32 v227, v123
	v_mfma_f32_32x32x16_bf16 v[80:95], v[68:71], v[148:151], v[80:95]
	ds_read_b128 v[68:71], v202 offset:6752
	v_exp_f32_e32 v229, v124
	v_exp_f32_e32 v231, v125
	v_exp_f32_e32 v233, v126
	v_exp_f32_e32 v235, v127
	s_and_b64 vcc, exec, s[8:9]
	s_waitcnt lgkmcnt(1)
	v_mfma_f32_32x32x16_bf16 v[80:95], v[64:67], v[152:155], v[80:95]
	s_waitcnt lgkmcnt(0)
	v_mfma_f32_32x32x16_bf16 v[80:95], v[68:71], v[156:159], v[80:95]
	v_mfma_f32_32x32x16_bf16 v[48:63], v[72:75], v[156:159], v[48:63]
	ds_read_b128 v[64:67], v202 offset:128
	ds_read_b128 v[96:99], v202 offset:160
	ds_read_b128 v[72:75], v202 offset:6784
	ds_read_b128 v[100:103], v202 offset:6816
	ds_read_b64_tr_b16 v[104:105], v175 offset:38912
	ds_read_b64_tr_b16 v[106:107], v175 offset:40448
	ds_read_b64_tr_b16 v[110:111], v175 offset:40512
	ds_read_b64_tr_b16 v[108:109], v175 offset:38976
	ds_read_b64_tr_b16 v[112:113], v175 offset:41984
	ds_read_b64_tr_b16 v[114:115], v175 offset:43520
	ds_read_b64_tr_b16 v[118:119], v175 offset:43584
	ds_read_b64_tr_b16 v[116:117], v175 offset:42048
	s_waitcnt lgkmcnt(8)
	v_mfma_f32_32x32x16_bf16 v[80:95], v[72:75], v[160:163], v[80:95]
	v_mfma_f32_32x32x16_bf16 v[48:63], v[64:67], v[160:163], v[48:63]
	v_mfma_f32_32x32x16_bf16 v[64:79], v[100:103], v[164:167], v[80:95]
	v_mfma_f32_32x32x16_bf16 v[48:63], v[96:99], v[164:167], v[48:63]
	v_add_f32_e64 v96, v184, v206
	v_add_f32_e64 v97, v185, v207
	v_add_f32_e64 v98, v208, v210
	v_add_f32_e64 v99, v209, v211
	v_pk_add_f32 v[96:97], v[96:97], v[98:99]
	v_pk_add_f32 v[98:99], v[212:213], v[214:215]
	s_nop 2
	v_cvt_pk_bf16_f32 v80, v184, v206
	v_cvt_pk_bf16_f32 v81, v208, v210
	v_cvt_pk_bf16_f32 v82, v212, v214
	v_cvt_pk_bf16_f32 v83, v216, v218
	v_cvt_pk_bf16_f32 v84, v185, v207
	v_cvt_pk_bf16_f32 v85, v209, v211
	v_cvt_pk_bf16_f32 v86, v213, v215
	s_waitcnt lgkmcnt(6)
	v_mfma_f32_32x32x16_bf16 v[16:31], v[104:107], v[80:83], v[16:31]
	v_cvt_pk_bf16_f32 v87, v217, v219
	v_add_f32_e64 v96, v96, 0
	v_add_f32_e64 v97, v97, 0
	v_cvt_pk_bf16_f32 v88, v220, v222
	v_cvt_pk_bf16_f32 v89, v224, v226
	v_cvt_pk_bf16_f32 v90, v228, v230
	v_cvt_pk_bf16_f32 v91, v232, v234
	v_cvt_pk_bf16_f32 v92, v221, v223
	s_waitcnt lgkmcnt(4)
	v_mfma_f32_32x32x16_bf16 v[0:15], v[108:111], v[80:83], v[0:15]
	v_add_f32_e64 v82, v220, v222
	v_add_f32_e64 v83, v221, v223
	v_cvt_pk_bf16_f32 v93, v225, v227
	v_cvt_pk_bf16_f32 v94, v229, v231
	v_cvt_pk_bf16_f32 v95, v233, v235
	v_add_f32_e64 v100, v216, v218
	v_add_f32_e64 v101, v217, v219
	v_add_f32_e64 v98, v98, v100
	v_add_f32_e64 v99, v99, v101
	v_add_f32_e64 v100, v232, v234
	v_add_f32_e64 v101, v233, v235
	v_pk_add_f32 v[80:81], v[98:99], 0 op_sel_hi:[1,0]
	v_pk_add_f32 v[98:99], v[224:225], v[226:227]
	s_nop 0
	v_pk_add_f32 v[82:83], v[82:83], v[98:99]
	v_pk_add_f32 v[98:99], v[228:229], v[230:231]
	s_waitcnt lgkmcnt(2)
	v_mfma_f32_32x32x16_bf16 v[16:31], v[112:115], v[84:87], v[16:31]
	v_add_f32_e64 v98, v98, v100
	v_add_f32_e64 v99, v99, v101
	v_add_f32_e64 v82, v82, v96
	v_add_f32_e64 v83, v83, v97
	v_add_f32_e64 v80, v98, v80
	v_add_f32_e64 v81, v99, v81
	v_max3_f32 v97, v48, v49, v50
	v_pk_add_f32 v[80:81], v[82:83], v[80:81]
	v_max3_f32 v99, v64, v65, v66
	v_add_f32_e32 v96, v80, v81
	s_waitcnt lgkmcnt(0)
	v_mfma_f32_32x32x16_bf16 v[0:15], v[116:119], v[84:87], v[0:15]
	ds_read_b64_tr_b16 v[80:81], v175 offset:45056
	ds_read_b64_tr_b16 v[82:83], v175 offset:46592
	v_max_f32_e32 v98, v51, v52
	ds_read_b64_tr_b16 v[86:87], v175 offset:46656
	ds_read_b64_tr_b16 v[84:85], v175 offset:45120
	v_max3_f32 v100, v67, v68, v69
	v_add_f32_e32 v205, v205, v96
	s_waitcnt lgkmcnt(2)
	v_mfma_f32_32x32x16_bf16 v[16:31], v[80:83], v[88:91], v[16:31]
	v_max3_f32 v80, v97, v54, v55
	v_max3_f32 v97, v98, v53, v56
	v_max3_f32 v98, v99, v70, v71
	v_max3_f32 v99, v100, v72, v73
	v_max3_f32 v100, v80, v58, v59
	ds_read_b64_tr_b16 v[80:81], v175 offset:48128
	ds_read_b64_tr_b16 v[82:83], v175 offset:49664
	s_waitcnt lgkmcnt(2)
	v_mfma_f32_32x32x16_bf16 v[0:15], v[84:87], v[88:91], v[0:15]
	v_max3_f32 v84, v98, v74, v75
	v_max3_f32 v91, v84, v78, v79
	ds_read_b64_tr_b16 v[86:87], v175 offset:49728
	ds_read_b64_tr_b16 v[84:85], v175 offset:48192
	v_max3_f32 v88, v97, v57, v60
	v_max3_f32 v89, v99, v76, v77
	v_max3_f32 v90, v100, v62, v63
	s_waitcnt lgkmcnt(2)
	v_mfma_f32_32x32x16_bf16 v[16:31], v[80:83], v[92:95], v[16:31]
	v_max3_f32 v80, v88, v61, v89
	v_max3_f32 v80, v90, v91, v80
	v_mov_b32_e32 v81, v80
	s_nop 1
	v_permlane32_swap_b32_e32 v80, v81
	s_waitcnt lgkmcnt(0)
	v_mfma_f32_32x32x16_bf16 v[0:15], v[84:87], v[92:95], v[0:15]
	s_cbranch_vccnz .LBB0_641
	v_max_f32_e32 v80, v80, v81
	v_cmp_lt_f32_e32 vcc, s45, v80
	s_cbranch_vccnz .LBB0_650

.LBB0_1757:
	ds_read_b128 v[112:115], v165 offset:9216
	ds_read_b128 v[116:119], v165 offset:9248
	v_lshl_add_u64 v[162:163], v[158:159], 0, s[8:9]
	v_exp_f32_e32 v208, v48
	v_add_co_u32_e32 v48, vcc, 0x6d90000, v162
	v_exp_f32_e32 v210, v49
	s_nop 0
	v_addc_co_u32_e32 v49, vcc, 0, v163, vcc
	s_waitcnt lgkmcnt(1)
	v_mfma_f32_32x32x16_bf16 v[96:111], v[112:115], v[130:133], v[32:47]
	ds_read_b128 v[178:181], v165 offset:13824
	ds_read_b128 v[182:185], v165 offset:13856
	ds_read_b128 v[112:115], v165 offset:9280
	ds_read_b128 v[196:199], v165 offset:9312
	ds_read_b128 v[200:203], v165 offset:13888
	ds_read_b128 v[204:207], v165 offset:13920
	global_load_dwordx4 v[150:153], v[48:49], off offset:2112
	v_exp_f32_e32 v212, v50
	v_exp_f32_e32 v214, v51
	v_exp_f32_e32 v216, v52
	v_exp_f32_e32 v218, v53
	v_exp_f32_e32 v220, v54
	s_waitcnt lgkmcnt(6)
	v_mfma_f32_32x32x16_bf16 v[96:111], v[116:119], v[134:137], v[96:111]
	v_exp_f32_e32 v222, v55
	v_exp_f32_e32 v209, v56
	v_exp_f32_e32 v211, v57
	v_exp_f32_e32 v213, v58
	v_exp_f32_e32 v215, v59
	v_exp_f32_e32 v217, v60
	v_exp_f32_e32 v219, v61
	s_waitcnt lgkmcnt(3)
	v_mfma_f32_32x32x16_bf16 v[96:111], v[112:115], v[138:141], v[96:111]
	v_exp_f32_e32 v221, v62
	v_exp_f32_e32 v223, v63
	v_mfma_f32_32x32x16_bf16 v[112:127], v[178:181], v[130:133], v[32:47]
	v_exp_f32_e32 v178, v64
	v_exp_f32_e32 v180, v65
	ds_read_b64_tr_b16 v[48:49], v175 offset:18432
	ds_read_b64_tr_b16 v[50:51], v175 offset:19968
	ds_read_b64_tr_b16 v[54:55], v175 offset:20032
	ds_read_b64_tr_b16 v[52:53], v175 offset:18496
	ds_read_b64_tr_b16 v[56:57], v175 offset:21504
	ds_read_b64_tr_b16 v[58:59], v175 offset:23040
	ds_read_b64_tr_b16 v[62:63], v175 offset:23104
	ds_read_b64_tr_b16 v[60:61], v175 offset:21568
	v_cvt_pk_bf16_f32 v64, v208, v210
	v_cvt_pk_bf16_f32 v65, v212, v214
	v_exp_f32_e32 v179, v72
	v_exp_f32_e32 v181, v73
	v_mfma_f32_32x32x16_bf16 v[112:127], v[182:185], v[134:137], v[112:127]
	v_exp_f32_e32 v182, v66
	v_exp_f32_e32 v184, v67
	v_cvt_pk_bf16_f32 v66, v216, v218
	v_cvt_pk_bf16_f32 v67, v220, v222
	v_exp_f32_e32 v183, v74
	v_exp_f32_e32 v185, v75
	v_exp_f32_e32 v224, v68
	s_waitcnt lgkmcnt(6)
	v_mfma_f32_32x32x16_bf16 v[16:31], v[48:51], v[64:67], v[16:31]
	v_exp_f32_e32 v226, v69
	v_exp_f32_e32 v228, v70
	v_exp_f32_e32 v230, v71
	v_exp_f32_e32 v225, v76
	v_exp_f32_e32 v227, v77
	v_exp_f32_e32 v229, v78
	v_exp_f32_e32 v231, v79
	s_waitcnt lgkmcnt(4)
	v_mfma_f32_32x32x16_bf16 v[0:15], v[52:55], v[64:67], v[0:15]
	v_add_f32_e64 v48, v208, v210
	v_add_f32_e64 v49, v209, v211
	v_add_f32_e64 v50, v212, v214
	v_add_f32_e64 v51, v213, v215
	v_add_f32_e64 v52, v178, v180
	v_add_f32_e64 v53, v179, v181
	v_pk_add_f32 v[48:49], v[48:49], v[50:51]
	v_pk_add_f32 v[50:51], v[216:217], v[218:219]
	v_pk_add_f32 v[54:55], v[182:183], v[184:185]
	v_cvt_pk_bf16_f32 v68, v209, v211
	v_mfma_f32_32x32x16_bf16 v[112:127], v[200:203], v[138:141], v[112:127]
	v_cvt_pk_bf16_f32 v69, v213, v215
	v_cvt_pk_bf16_f32 v70, v217, v219
	v_cvt_pk_bf16_f32 v71, v221, v223
	v_add_f32_e64 v52, v52, v54
	v_add_f32_e64 v53, v53, v55
	v_pk_add_f32 v[54:55], v[224:225], v[226:227]
	v_pk_add_f32 v[64:65], v[228:229], v[230:231]
	v_mfma_f32_32x32x16_bf16 v[96:111], v[196:199], v[142:145], v[96:111]
	v_add_f32_e64 v196, v220, v222
	v_add_f32_e64 v197, v221, v223
	v_add_f32_e64 v54, v54, v64
	v_add_f32_e64 v55, v55, v65
	v_add_f32_e64 v50, v50, v196
	v_add_f32_e64 v51, v51, v197
	v_pk_add_f32 v[48:49], v[48:49], v[52:53]
	v_cvt_pk_bf16_f32 v72, v178, v180
	v_pk_add_f32 v[50:51], v[50:51], v[54:55]
	s_waitcnt lgkmcnt(2)
	v_mfma_f32_32x32x16_bf16 v[16:31], v[56:59], v[68:71], v[16:31]
	v_add_f32_e64 v48, v48, v50
	v_add_f32_e64 v49, v49, v51
	v_add_f32_e32 v56, v48, v49
	ds_read_b64_tr_b16 v[48:49], v175 offset:24576
	ds_read_b64_tr_b16 v[50:51], v175 offset:26112
	v_max_f32_e32 v58, v99, v100
	ds_read_b64_tr_b16 v[54:55], v175 offset:26176
	ds_read_b64_tr_b16 v[52:53], v175 offset:24640
	s_waitcnt lgkmcnt(4)
	v_mfma_f32_32x32x16_bf16 v[0:15], v[60:63], v[68:71], v[0:15]
	v_cvt_pk_bf16_f32 v73, v182, v184
	v_cvt_pk_bf16_f32 v74, v224, v226
	v_cvt_pk_bf16_f32 v75, v228, v230
	v_max3_f32 v57, v96, v97, v98
	v_max3_f32 v57, v57, v102, v103
	v_max3_f32 v58, v58, v101, v104
	v_cvt_pk_bf16_f32 v76, v179, v181
	v_mfma_f32_32x32x16_bf16 v[112:127], v[204:207], v[142:145], v[112:127]
	v_cvt_pk_bf16_f32 v77, v183, v185
	v_cvt_pk_bf16_f32 v78, v225, v227
	v_cvt_pk_bf16_f32 v79, v229, v231
	v_add_f32_e32 v176, v176, v56
	s_waitcnt lgkmcnt(2)
	v_mfma_f32_32x32x16_bf16 v[16:31], v[48:51], v[72:75], v[16:31]
	s_nop 5
	v_max3_f32 v59, v112, v113, v114
	v_max3_f32 v48, v115, v116, v117
	v_max3_f32 v59, v59, v118, v119
	v_max3_f32 v60, v48, v120, v121
	ds_read_b64_tr_b16 v[48:49], v175 offset:27648
	ds_read_b64_tr_b16 v[50:51], v175 offset:29184
	s_waitcnt lgkmcnt(2)
	v_mfma_f32_32x32x16_bf16 v[0:15], v[52:55], v[72:75], v[0:15]
	v_max3_f32 v52, v57, v106, v107
	v_max3_f32 v57, v58, v105, v108
	v_max3_f32 v58, v59, v122, v123
	v_max3_f32 v59, v60, v124, v125
	v_max3_f32 v60, v52, v110, v111
	ds_read_b64_tr_b16 v[54:55], v175 offset:29248
	ds_read_b64_tr_b16 v[52:53], v175 offset:27712
	s_waitcnt lgkmcnt(2)
	v_mfma_f32_32x32x16_bf16 v[16:31], v[48:51], v[76:79], v[16:31]
	v_max3_f32 v48, v58, v126, v127
	v_max3_f32 v49, v57, v109, v59
	v_max3_f32 v48, v60, v48, v49
	v_mov_b32_e32 v49, v48
	s_nop 1
	v_permlane32_swap_b32_e32 v48, v49
	v_max_f32_e32 v49, v49, v49
	s_waitcnt lgkmcnt(0)
	v_mfma_f32_32x32x16_bf16 v[0:15], v[52:55], v[76:79], v[0:15]
	v_max_f32_e32 v48, v48, v48
	v_max_f32_e32 v48, v48, v49
	v_cmp_lt_f32_e32 vcc, s51, v48
	s_cbranch_vccnz .LBB0_1770
	v_cndmask_b32_e64 v48, 0, 1, s[40:41]
	v_cmp_ne_u32_e64 s[2:3], 1, v48
	s_andn2_b64 vcc, exec, s[40:41]
	s_cbranch_vccnz .LBB0_1760

.LBB0_1764:
	ds_read_b128 v[64:67], v165
	ds_read_b128 v[68:71], v165 offset:32
	ds_read_b128 v[72:75], v165 offset:4608
	ds_read_b128 v[76:79], v165 offset:4640
	v_exp_f32_e32 v196, v96
	s_waitcnt lgkmcnt(3)
	v_mfma_f32_32x32x16_bf16 v[48:63], v[64:67], v[130:133], v[32:47]
	ds_read_b128 v[64:67], v165 offset:64
	ds_read_b128 v[160:163], v165 offset:96
	ds_read_b128 v[178:181], v165 offset:4672
	ds_read_b128 v[182:185], v165 offset:4704
	v_exp_f32_e32 v198, v97
	v_exp_f32_e32 v200, v98
	v_exp_f32_e32 v202, v99
	v_exp_f32_e32 v204, v100
	v_exp_f32_e32 v206, v101
	v_exp_f32_e32 v208, v102
	s_waitcnt lgkmcnt(5)
	v_mfma_f32_32x32x16_bf16 v[80:95], v[72:75], v[130:133], v[32:47]
	v_exp_f32_e32 v210, v103
	v_exp_f32_e32 v197, v104
	v_exp_f32_e32 v199, v105
	v_exp_f32_e32 v201, v106
	v_exp_f32_e32 v203, v107
	v_exp_f32_e32 v205, v108
	v_exp_f32_e32 v207, v109
	s_waitcnt lgkmcnt(4)
	v_mfma_f32_32x32x16_bf16 v[80:95], v[76:79], v[134:137], v[80:95]
	v_exp_f32_e32 v209, v110
	v_exp_f32_e32 v211, v111
	ds_read_b64_tr_b16 v[96:97], v175 offset:30720
	ds_read_b64_tr_b16 v[98:99], v175 offset:32256
	ds_read_b64_tr_b16 v[102:103], v175 offset:32320
	ds_read_b64_tr_b16 v[100:101], v175 offset:30784
	ds_read_b64_tr_b16 v[104:105], v175 offset:33792
	ds_read_b64_tr_b16 v[106:107], v175 offset:35328
	ds_read_b64_tr_b16 v[110:111], v175 offset:35392
	ds_read_b64_tr_b16 v[108:109], v175 offset:33856
	v_exp_f32_e32 v112, v112
	v_exp_f32_e32 v212, v113
	v_exp_f32_e32 v114, v114
	v_exp_f32_e32 v214, v115
	v_mfma_f32_32x32x16_bf16 v[48:63], v[68:71], v[134:137], v[48:63]
	v_exp_f32_e32 v113, v120
	v_exp_f32_e32 v213, v121
	v_exp_f32_e32 v115, v122
	v_exp_f32_e32 v215, v123
	v_exp_f32_e32 v116, v116
	v_exp_f32_e32 v216, v117
	v_exp_f32_e32 v118, v118
	s_waitcnt lgkmcnt(8)
	v_mfma_f32_32x32x16_bf16 v[80:95], v[178:181], v[138:141], v[80:95]
	v_mfma_f32_32x32x16_bf16 v[48:63], v[64:67], v[138:141], v[48:63]
	v_mfma_f32_32x32x16_bf16 v[64:79], v[182:185], v[142:145], v[80:95]
	v_mfma_f32_32x32x16_bf16 v[48:63], v[160:163], v[142:145], v[48:63]
	v_exp_f32_e32 v218, v119
	v_exp_f32_e32 v117, v124
	v_exp_f32_e32 v217, v125
	v_exp_f32_e32 v119, v126
	v_exp_f32_e32 v219, v127
	v_pk_add_f32 v[120:121], v[208:209], v[210:211]
	s_and_b64 vcc, exec, s[2:3]
	s_nop 1
	v_cvt_pk_bf16_f32 v80, v196, v198
	v_cvt_pk_bf16_f32 v81, v200, v202
	v_cvt_pk_bf16_f32 v82, v204, v206
	v_cvt_pk_bf16_f32 v83, v208, v210
	v_cvt_pk_bf16_f32 v84, v197, v199
	v_cvt_pk_bf16_f32 v85, v201, v203
	v_cvt_pk_bf16_f32 v86, v205, v207
	v_cvt_pk_bf16_f32 v87, v209, v211
	v_cvt_pk_bf16_f32 v88, v112, v212
	v_cvt_pk_bf16_f32 v89, v114, v214
	v_cvt_pk_bf16_f32 v90, v116, v216
	s_waitcnt lgkmcnt(6)
	v_mfma_f32_32x32x16_bf16 v[16:31], v[96:99], v[80:83], v[16:31]
	v_add_f32_e64 v96, v196, v198
	v_add_f32_e64 v97, v197, v199
	v_add_f32_e64 v98, v200, v202
	v_add_f32_e64 v99, v201, v203
	v_cvt_pk_bf16_f32 v91, v118, v218
	v_pk_add_f32 v[96:97], v[96:97], v[98:99]
	v_pk_add_f32 v[98:99], v[204:205], v[206:207]
	v_pk_add_f32 v[98:99], v[98:99], v[120:121]
	s_waitcnt lgkmcnt(4)
	v_mfma_f32_32x32x16_bf16 v[0:15], v[100:103], v[80:83], v[0:15]
	v_add_f32_e64 v80, v98, 0
	v_add_f32_e64 v81, v99, 0
	v_add_f32_e64 v82, v112, v212
	v_add_f32_e64 v83, v113, v213
	v_add_f32_e64 v98, v114, v214
	v_add_f32_e64 v99, v115, v215
	v_pk_add_f32 v[100:101], v[118:119], v[218:219]
	v_pk_add_f32 v[82:83], v[82:83], v[98:99]
	v_pk_add_f32 v[98:99], v[116:117], v[216:217]
	v_pk_add_f32 v[82:83], v[82:83], v[96:97]
	v_add_f32_e64 v98, v98, v100
	v_add_f32_e64 v99, v99, v101
	v_max3_f32 v97, v48, v49, v50
	v_add_f32_e64 v80, v98, v80
	v_add_f32_e64 v81, v99, v81
	v_cvt_pk_bf16_f32 v92, v113, v213
	v_pk_add_f32 v[80:81], v[82:83], v[80:81]
	v_cvt_pk_bf16_f32 v93, v115, v215
	v_add_f32_e32 v96, v80, v81
	s_waitcnt lgkmcnt(2)
	v_mfma_f32_32x32x16_bf16 v[16:31], v[104:107], v[84:87], v[16:31]
	ds_read_b64_tr_b16 v[80:81], v175 offset:36864
	ds_read_b64_tr_b16 v[82:83], v175 offset:38400
	v_max3_f32 v99, v64, v65, v66
	v_max3_f32 v100, v67, v68, v69
	v_cvt_pk_bf16_f32 v94, v117, v217
	v_cvt_pk_bf16_f32 v95, v119, v219
	v_add_f32_e32 v176, v176, v96
	s_waitcnt lgkmcnt(2)
	v_mfma_f32_32x32x16_bf16 v[0:15], v[108:111], v[84:87], v[0:15]
	v_max_f32_e32 v98, v51, v52
	ds_read_b64_tr_b16 v[86:87], v175 offset:38464
	ds_read_b64_tr_b16 v[84:85], v175 offset:36928
	s_waitcnt lgkmcnt(2)
	v_mfma_f32_32x32x16_bf16 v[16:31], v[80:83], v[88:91], v[16:31]
	v_max3_f32 v80, v97, v54, v55
	v_max3_f32 v97, v98, v53, v56
	v_max3_f32 v98, v99, v70, v71
	v_max3_f32 v99, v100, v72, v73
	v_max3_f32 v100, v80, v58, v59
	ds_read_b64_tr_b16 v[80:81], v175 offset:39936
	ds_read_b64_tr_b16 v[82:83], v175 offset:41472
	s_waitcnt lgkmcnt(2)
	v_mfma_f32_32x32x16_bf16 v[0:15], v[84:87], v[88:91], v[0:15]
	v_max3_f32 v84, v98, v74, v75
	v_max3_f32 v91, v84, v78, v79
	ds_read_b64_tr_b16 v[86:87], v175 offset:41536
	ds_read_b64_tr_b16 v[84:85], v175 offset:40000
	v_max3_f32 v88, v97, v57, v60
	v_max3_f32 v89, v99, v76, v77
	v_max3_f32 v90, v100, v62, v63
	s_waitcnt lgkmcnt(2)
	v_mfma_f32_32x32x16_bf16 v[16:31], v[80:83], v[92:95], v[16:31]
	v_max3_f32 v80, v88, v61, v89
	v_max3_f32 v80, v90, v91, v80
	v_mov_b32_e32 v81, v80
	s_nop 1
	v_permlane32_swap_b32_e32 v80, v81
	s_waitcnt lgkmcnt(0)
	v_mfma_f32_32x32x16_bf16 v[0:15], v[84:87], v[92:95], v[0:15]
	s_cbranch_vccnz .LBB0_1766
	v_max_f32_e32 v80, v80, v81
	v_cmp_lt_f32_e32 vcc, s51, v80
	s_cbranch_vccnz .LBB0_1771

.LBB0_1850:
	ds_read_b128 v[80:83], v203 offset:13312
	ds_read_b128 v[84:87], v203 offset:13344
	s_waitcnt vmcnt(0)
	ds_read_b128 v[164:167], v203 offset:19968
	ds_read_b128 v[208:211], v203 offset:20000
	ds_read_b128 v[212:215], v203 offset:13376
	v_lshl_add_u64 v[184:185], s[74:75], 0, v[182:183]
	s_waitcnt lgkmcnt(4)
	v_mfma_f32_32x32x16_bf16 v[96:111], v[80:83], v[140:143], v[32:47]
	ds_read_b128 v[216:219], v203 offset:13408
	v_exp_f32_e32 v220, v48
	v_exp_f32_e32 v222, v49
	v_exp_f32_e32 v224, v50
	v_exp_f32_e32 v226, v51
	ds_read_b128 v[48:51], v203 offset:20064
	v_exp_f32_e32 v228, v52
	s_waitcnt lgkmcnt(4)
	v_mfma_f32_32x32x16_bf16 v[112:127], v[164:167], v[140:143], v[32:47]
	v_add_co_u32_e32 v164, vcc, 0xf588000, v184
	v_exp_f32_e32 v230, v53
	s_nop 0
	v_addc_co_u32_e32 v165, vcc, 0, v185, vcc
	global_load_dwordx4 v[164:167], v[164:165], off offset:1664
	v_exp_f32_e32 v232, v54
	v_mfma_f32_32x32x16_bf16 v[96:111], v[84:87], v[144:147], v[96:111]
	v_exp_f32_e32 v234, v55
	v_exp_f32_e32 v221, v56
	v_exp_f32_e32 v223, v57
	v_exp_f32_e32 v225, v58
	v_exp_f32_e32 v227, v59
	v_exp_f32_e32 v229, v60
	v_exp_f32_e32 v231, v61
	s_waitcnt lgkmcnt(2)
	v_mfma_f32_32x32x16_bf16 v[96:111], v[212:215], v[148:151], v[96:111]
	ds_read_b128 v[212:215], v203 offset:20032
	ds_read_b128 v[52:55], v203 offset:13440
	ds_read_b128 v[56:59], v203 offset:13472
	v_exp_f32_e32 v233, v62
	v_exp_f32_e32 v235, v63
	v_exp_f32_e32 v236, v68
	v_exp_f32_e32 v238, v69
	v_exp_f32_e32 v240, v70
	v_mfma_f32_32x32x16_bf16 v[112:127], v[208:211], v[144:147], v[112:127]
	ds_read_b128 v[60:63], v203 offset:20096
	ds_read_b128 v[208:211], v203 offset:20128
	v_exp_f32_e32 v242, v71
	v_cvt_pk_bf16_f32 v68, v220, v222
	v_cvt_pk_bf16_f32 v69, v224, v226
	v_cvt_pk_bf16_f32 v70, v228, v230
	v_cvt_pk_bf16_f32 v71, v232, v234
	v_exp_f32_e32 v237, v76
	s_waitcnt lgkmcnt(4)
	v_mfma_f32_32x32x16_bf16 v[112:127], v[212:215], v[148:151], v[112:127]
	v_exp_f32_e32 v212, v64
	v_exp_f32_e32 v214, v65
	v_exp_f32_e32 v213, v72
	v_exp_f32_e32 v215, v73
	v_exp_f32_e32 v239, v77
	v_exp_f32_e32 v241, v78
	v_exp_f32_e32 v243, v79
	v_mfma_f32_32x32x16_bf16 v[96:111], v[216:219], v[152:155], v[96:111]
	v_exp_f32_e32 v216, v66
	v_exp_f32_e32 v218, v67
	v_exp_f32_e32 v217, v74
	v_exp_f32_e32 v219, v75
	v_cvt_pk_bf16_f32 v72, v221, v223
	v_cvt_pk_bf16_f32 v73, v225, v227
	v_cvt_pk_bf16_f32 v74, v229, v231
	v_mfma_f32_32x32x16_bf16 v[112:127], v[48:51], v[152:155], v[112:127]
	v_cvt_pk_bf16_f32 v75, v233, v235
	v_cvt_pk_bf16_f32 v76, v213, v215
	v_cvt_pk_bf16_f32 v77, v217, v219
	v_cvt_pk_bf16_f32 v78, v237, v239
	v_cvt_pk_bf16_f32 v79, v241, v243
	s_waitcnt lgkmcnt(3)
	v_mfma_f32_32x32x16_bf16 v[96:111], v[52:55], v[156:159], v[96:111]
	ds_read_b64_tr_b16 v[48:49], v175 offset:26624
	ds_read_b64_tr_b16 v[50:51], v175 offset:28160
	ds_read_b64_tr_b16 v[54:55], v175 offset:28224
	ds_read_b64_tr_b16 v[52:53], v175 offset:26688
	s_waitcnt lgkmcnt(5)
	v_mfma_f32_32x32x16_bf16 v[112:127], v[60:63], v[156:159], v[112:127]
	ds_read_b64_tr_b16 v[60:61], v175 offset:29696
	ds_read_b64_tr_b16 v[62:63], v175 offset:31232
	ds_read_b64_tr_b16 v[66:67], v175 offset:31296
	ds_read_b64_tr_b16 v[64:65], v175 offset:29760
	s_waitcnt lgkmcnt(6)
	v_mfma_f32_32x32x16_bf16 v[16:31], v[48:51], v[68:71], v[16:31]
	v_add_f32_e64 v48, v228, v230
	v_add_f32_e64 v49, v229, v231
	v_add_f32_e64 v50, v232, v234
	v_add_f32_e64 v51, v233, v235
	v_add_f32_e64 v48, v48, v50
	v_add_f32_e64 v49, v49, v51
	s_waitcnt lgkmcnt(4)
	v_mfma_f32_32x32x16_bf16 v[0:15], v[52:55], v[68:71], v[0:15]
	v_add_f32_e64 v54, v236, v238
	v_add_f32_e64 v55, v237, v239
	v_add_f32_e64 v68, v240, v242
	v_add_f32_e64 v69, v241, v243
	v_add_f32_e64 v54, v54, v68
	v_add_f32_e64 v55, v55, v69
	v_pk_add_f32 v[48:49], v[48:49], v[54:55]
	v_mfma_f32_32x32x16_bf16 v[96:111], v[56:59], v[160:163], v[96:111]
	v_cvt_pk_bf16_f32 v56, v212, v214
	v_cvt_pk_bf16_f32 v57, v216, v218
	v_cvt_pk_bf16_f32 v58, v236, v238
	v_cvt_pk_bf16_f32 v59, v240, v242
	v_mfma_f32_32x32x16_bf16 v[112:127], v[208:211], v[160:163], v[112:127]
	v_add_f32_e64 v208, v220, v222
	v_add_f32_e64 v209, v221, v223
	v_add_f32_e64 v210, v224, v226
	v_add_f32_e64 v211, v225, v227
	v_add_f32_e64 v208, v208, v210
	v_add_f32_e64 v209, v209, v211
	v_pk_add_f32 v[210:211], v[216:217], v[218:219]
	v_pk_add_f32 v[50:51], v[208:209], 0 op_sel_hi:[1,0]
	v_pk_add_f32 v[208:209], v[212:213], v[214:215]
	s_waitcnt lgkmcnt(2)
	v_mfma_f32_32x32x16_bf16 v[16:31], v[60:63], v[72:75], v[16:31]
	v_add_f32_e64 v52, v208, v210
	v_add_f32_e64 v53, v209, v211
	v_max3_f32 v54, v112, v113, v114
	v_add_f32_e64 v50, v50, v52
	v_add_f32_e64 v51, v51, v53
	v_max3_f32 v52, v96, v97, v98
	v_pk_add_f32 v[48:49], v[50:51], v[48:49]
	v_max3_f32 v62, v52, v102, v103
	v_add_f32_e32 v60, v48, v49
	s_waitcnt lgkmcnt(0)
	v_mfma_f32_32x32x16_bf16 v[0:15], v[64:67], v[72:75], v[0:15]
	v_max_f32_e32 v53, v99, v100
	ds_read_b64_tr_b16 v[48:49], v175 offset:32768
	ds_read_b64_tr_b16 v[50:51], v175 offset:34304
	v_max3_f32 v63, v53, v101, v104
	v_max3_f32 v64, v54, v118, v119
	ds_read_b64_tr_b16 v[54:55], v175 offset:34368
	ds_read_b64_tr_b16 v[52:53], v175 offset:32832
	v_max3_f32 v61, v115, v116, v117
	s_waitcnt lgkmcnt(2)
	v_mfma_f32_32x32x16_bf16 v[16:31], v[48:51], v[56:59], v[16:31]
	v_max3_f32 v48, v61, v120, v121
	v_max3_f32 v61, v62, v106, v107
	v_max3_f32 v62, v63, v105, v108
	v_max3_f32 v63, v64, v122, v123
	v_max3_f32 v64, v48, v124, v125
	ds_read_b64_tr_b16 v[48:49], v175 offset:35840
	ds_read_b64_tr_b16 v[50:51], v175 offset:37376
	v_add_f32_e32 v206, v206, v60
	s_waitcnt lgkmcnt(2)
	v_mfma_f32_32x32x16_bf16 v[0:15], v[52:55], v[56:59], v[0:15]
	v_max3_f32 v52, v61, v110, v111
	v_max3_f32 v53, v63, v126, v127
	v_max3_f32 v54, v62, v109, v64
	v_max3_f32 v56, v52, v53, v54
	ds_read_b64_tr_b16 v[54:55], v175 offset:37440
	ds_read_b64_tr_b16 v[52:53], v175 offset:35904
	v_mov_b32_e32 v57, v56
	s_nop 1
	v_permlane32_swap_b32_e32 v56, v57
	s_waitcnt lgkmcnt(2)
	v_mfma_f32_32x32x16_bf16 v[16:31], v[48:51], v[76:79], v[16:31]
	v_max_f32_e32 v48, v57, v57
	v_max_f32_e32 v49, v56, v56
	v_max_f32_e32 v48, v49, v48
	v_cmp_lt_f32_e32 vcc, s51, v48
	s_waitcnt lgkmcnt(0)
	v_mfma_f32_32x32x16_bf16 v[0:15], v[52:55], v[76:79], v[0:15]
	s_cbranch_vccnz .LBB0_1879
	v_cndmask_b32_e64 v48, 0, 1, s[40:41]
	v_cmp_ne_u32_e64 s[8:9], 1, v48
	s_andn2_b64 vcc, exec, s[40:41]
	s_cbranch_vccnz .LBB0_1855

.LBB0_1869:
	ds_read_b128 v[64:67], v203
	ds_read_b128 v[68:71], v203 offset:32
	v_exp_f32_e32 v184, v96
	v_exp_f32_e32 v208, v97
	v_exp_f32_e32 v210, v98
	s_waitcnt lgkmcnt(1)
	v_mfma_f32_32x32x16_bf16 v[48:63], v[64:67], v[140:143], v[32:47]
	v_exp_f32_e32 v212, v99
	v_exp_f32_e32 v214, v100
	v_exp_f32_e32 v216, v101
	v_exp_f32_e32 v218, v102
	v_exp_f32_e32 v220, v103
	v_exp_f32_e32 v185, v104
	v_exp_f32_e32 v209, v105
	s_waitcnt lgkmcnt(0)
	v_mfma_f32_32x32x16_bf16 v[48:63], v[68:71], v[144:147], v[48:63]
	ds_read_b128 v[64:67], v203 offset:6656
	ds_read_b128 v[68:71], v203 offset:6688
	v_exp_f32_e32 v211, v106
	v_exp_f32_e32 v213, v107
	v_exp_f32_e32 v215, v108
	v_exp_f32_e32 v217, v109
	v_exp_f32_e32 v219, v110
	v_exp_f32_e32 v221, v111
	s_waitcnt lgkmcnt(1)
	v_mfma_f32_32x32x16_bf16 v[80:95], v[64:67], v[140:143], v[32:47]
	ds_read_b128 v[64:67], v203 offset:64
	ds_read_b128 v[72:75], v203 offset:96
	v_exp_f32_e32 v222, v112
	v_exp_f32_e32 v224, v113
	v_exp_f32_e32 v226, v114
	v_exp_f32_e32 v228, v115
	v_exp_f32_e32 v230, v116
	v_exp_f32_e32 v232, v117
	s_waitcnt lgkmcnt(1)
	v_mfma_f32_32x32x16_bf16 v[48:63], v[64:67], v[148:151], v[48:63]
	ds_read_b128 v[64:67], v203 offset:6720
	v_exp_f32_e32 v234, v118
	v_exp_f32_e32 v236, v119
	v_exp_f32_e32 v223, v120
	v_exp_f32_e32 v225, v121
	v_exp_f32_e32 v227, v122
	v_exp_f32_e32 v229, v123
	v_mfma_f32_32x32x16_bf16 v[80:95], v[68:71], v[144:147], v[80:95]
	ds_read_b128 v[68:71], v203 offset:6752
	v_exp_f32_e32 v231, v124
	v_exp_f32_e32 v233, v125
	v_exp_f32_e32 v235, v126
	v_exp_f32_e32 v237, v127
	s_and_b64 vcc, exec, s[8:9]
	s_waitcnt lgkmcnt(1)
	v_mfma_f32_32x32x16_bf16 v[80:95], v[64:67], v[148:151], v[80:95]
	s_waitcnt lgkmcnt(0)
	v_mfma_f32_32x32x16_bf16 v[80:95], v[68:71], v[152:155], v[80:95]
	v_mfma_f32_32x32x16_bf16 v[48:63], v[72:75], v[152:155], v[48:63]
	ds_read_b128 v[64:67], v203 offset:128
	ds_read_b128 v[96:99], v203 offset:160
	ds_read_b128 v[72:75], v203 offset:6784
	ds_read_b128 v[100:103], v203 offset:6816
	ds_read_b64_tr_b16 v[104:105], v175 offset:38912
	ds_read_b64_tr_b16 v[106:107], v175 offset:40448
	ds_read_b64_tr_b16 v[110:111], v175 offset:40512
	ds_read_b64_tr_b16 v[108:109], v175 offset:38976
	ds_read_b64_tr_b16 v[112:113], v175 offset:41984
	ds_read_b64_tr_b16 v[114:115], v175 offset:43520
	ds_read_b64_tr_b16 v[118:119], v175 offset:43584
	ds_read_b64_tr_b16 v[116:117], v175 offset:42048
	s_waitcnt lgkmcnt(8)
	v_mfma_f32_32x32x16_bf16 v[80:95], v[72:75], v[156:159], v[80:95]
	v_mfma_f32_32x32x16_bf16 v[48:63], v[64:67], v[156:159], v[48:63]
	v_mfma_f32_32x32x16_bf16 v[64:79], v[100:103], v[160:163], v[80:95]
	v_mfma_f32_32x32x16_bf16 v[48:63], v[96:99], v[160:163], v[48:63]
	v_add_f32_e64 v96, v184, v208
	v_add_f32_e64 v97, v185, v209
	v_add_f32_e64 v98, v210, v212
	v_add_f32_e64 v99, v211, v213
	v_pk_add_f32 v[96:97], v[96:97], v[98:99]
	v_pk_add_f32 v[98:99], v[214:215], v[216:217]
	s_nop 2
	v_cvt_pk_bf16_f32 v80, v184, v208
	v_cvt_pk_bf16_f32 v81, v210, v212
	v_cvt_pk_bf16_f32 v82, v214, v216
	v_cvt_pk_bf16_f32 v83, v218, v220
	v_cvt_pk_bf16_f32 v84, v185, v209
	v_cvt_pk_bf16_f32 v85, v211, v213
	v_cvt_pk_bf16_f32 v86, v215, v217
	s_waitcnt lgkmcnt(6)
	v_mfma_f32_32x32x16_bf16 v[16:31], v[104:107], v[80:83], v[16:31]
	v_cvt_pk_bf16_f32 v87, v219, v221
	v_add_f32_e64 v96, v96, 0
	v_add_f32_e64 v97, v97, 0
	v_cvt_pk_bf16_f32 v88, v222, v224
	v_cvt_pk_bf16_f32 v89, v226, v228
	v_cvt_pk_bf16_f32 v90, v230, v232
	v_cvt_pk_bf16_f32 v91, v234, v236
	v_cvt_pk_bf16_f32 v92, v223, v225
	s_waitcnt lgkmcnt(4)
	v_mfma_f32_32x32x16_bf16 v[0:15], v[108:111], v[80:83], v[0:15]
	v_add_f32_e64 v82, v222, v224
	v_add_f32_e64 v83, v223, v225
	v_cvt_pk_bf16_f32 v93, v227, v229
	v_cvt_pk_bf16_f32 v94, v231, v233
	v_cvt_pk_bf16_f32 v95, v235, v237
	v_add_f32_e64 v100, v218, v220
	v_add_f32_e64 v101, v219, v221
	v_add_f32_e64 v98, v98, v100
	v_add_f32_e64 v99, v99, v101
	v_add_f32_e64 v100, v234, v236
	v_add_f32_e64 v101, v235, v237
	v_pk_add_f32 v[80:81], v[98:99], 0 op_sel_hi:[1,0]
	v_pk_add_f32 v[98:99], v[226:227], v[228:229]
	s_nop 0
	v_pk_add_f32 v[82:83], v[82:83], v[98:99]
	v_pk_add_f32 v[98:99], v[230:231], v[232:233]
	s_waitcnt lgkmcnt(2)
	v_mfma_f32_32x32x16_bf16 v[16:31], v[112:115], v[84:87], v[16:31]
	v_add_f32_e64 v98, v98, v100
	v_add_f32_e64 v99, v99, v101
	v_add_f32_e64 v82, v82, v96
	v_add_f32_e64 v83, v83, v97
	v_add_f32_e64 v80, v98, v80
	v_add_f32_e64 v81, v99, v81
	v_max3_f32 v97, v48, v49, v50
	v_pk_add_f32 v[80:81], v[82:83], v[80:81]
	v_max3_f32 v99, v64, v65, v66
	v_add_f32_e32 v96, v80, v81
	s_waitcnt lgkmcnt(0)
	v_mfma_f32_32x32x16_bf16 v[0:15], v[116:119], v[84:87], v[0:15]
	ds_read_b64_tr_b16 v[80:81], v175 offset:45056
	ds_read_b64_tr_b16 v[82:83], v175 offset:46592
	v_max_f32_e32 v98, v51, v52
	ds_read_b64_tr_b16 v[86:87], v175 offset:46656
	ds_read_b64_tr_b16 v[84:85], v175 offset:45120
	v_max3_f32 v100, v67, v68, v69
	v_add_f32_e32 v206, v206, v96
	s_waitcnt lgkmcnt(2)
	v_mfma_f32_32x32x16_bf16 v[16:31], v[80:83], v[88:91], v[16:31]
	v_max3_f32 v80, v97, v54, v55
	v_max3_f32 v97, v98, v53, v56
	v_max3_f32 v98, v99, v70, v71
	v_max3_f32 v99, v100, v72, v73
	v_max3_f32 v100, v80, v58, v59
	ds_read_b64_tr_b16 v[80:81], v175 offset:48128
	ds_read_b64_tr_b16 v[82:83], v175 offset:49664
	s_waitcnt lgkmcnt(2)
	v_mfma_f32_32x32x16_bf16 v[0:15], v[84:87], v[88:91], v[0:15]
	v_max3_f32 v84, v98, v74, v75
	v_max3_f32 v91, v84, v78, v79
	ds_read_b64_tr_b16 v[86:87], v175 offset:49728
	ds_read_b64_tr_b16 v[84:85], v175 offset:48192
	v_max3_f32 v88, v97, v57, v60
	v_max3_f32 v89, v99, v76, v77
	v_max3_f32 v90, v100, v62, v63
	s_waitcnt lgkmcnt(2)
	v_mfma_f32_32x32x16_bf16 v[16:31], v[80:83], v[92:95], v[16:31]
	v_max3_f32 v80, v88, v61, v89
	v_max3_f32 v80, v90, v91, v80
	v_mov_b32_e32 v81, v80
	s_nop 1
	v_permlane32_swap_b32_e32 v80, v81
	s_waitcnt lgkmcnt(0)
	v_mfma_f32_32x32x16_bf16 v[0:15], v[84:87], v[92:95], v[0:15]
	s_cbranch_vccnz .LBB0_1871
	v_max_f32_e32 v80, v80, v81
	v_cmp_lt_f32_e32 vcc, s51, v80
	s_cbranch_vccnz .LBB0_1880
